# speedup vs baseline: 1.0260x; 1.0036x over previous
; template <bool PERM, class SchedT, class Epi>
; __device__ __forceinline__ void gemm_phase(LAS unsigned char* lds, const SchedT& S, const Epi& E) {
;     ...
;         for (int a = 0; a < 2; ++a)
; #pragma unroll
;             for (int b = 0; b < 2; ++b)
; #pragma unroll
;                 for (int m = 0; m < 4; ++m)
; #pragma unroll
;                     for (int n = 0; n < 2; ++n) acc[a][b][m][n] = (f32x4){0.f, 0.f, 0.f, 0.f};
;         cur = nxt; cA = nA; cB = nB; lda = nlda; K = nK; ++ui;
.LBB0_43:
	s_lshr_b32 s9, s44, 6
	s_mov_b32 s21, s73
	s_add_i32 s45, s9, -2
	s_lshl_b64 s[26:27], s[20:21], 8
	s_add_u32 s22, s22, 0x80
	s_addc_u32 s23, s23, 0
	s_add_u32 s21, s24, 0x100
	s_addc_u32 s46, s25, 0
	v_mad_u64_u32 v[2:3], s[24:25], s20, v139, v[0:1]
	v_mov_b32_e32 v3, v1
	v_lshl_add_u64 v[130:131], s[26:27], 0, v[2:3]
	v_mad_u64_u32 v[2:3], s[24:25], s20, v141, v[142:143]
	v_mov_b32_e32 v3, v1
	v_lshl_add_u64 v[132:133], s[26:27], 0, v[2:3]
	s_mov_b32 s47, 0
	v_mov_b64_e32 v[2:3], 0
	v_mov_b64_e32 v[4:5], 0
	v_mov_b64_e32 v[6:7], 0
	v_mov_b64_e32 v[8:9], 0
	v_mov_b64_e32 v[10:11], 0
	v_mov_b64_e32 v[12:13], 0
	v_mov_b64_e32 v[14:15], 0
	v_mov_b64_e32 v[16:17], 0
	v_mov_b64_e32 v[18:19], 0
	v_mov_b64_e32 v[20:21], 0
	v_mov_b64_e32 v[22:23], 0
	v_mov_b64_e32 v[24:25], 0
	v_mov_b64_e32 v[26:27], 0
	v_mov_b64_e32 v[28:29], 0
	v_mov_b64_e32 v[30:31], 0
	v_mov_b64_e32 v[32:33], 0
	v_mov_b64_e32 v[34:35], 0
	v_mov_b64_e32 v[36:37], 0
	v_mov_b64_e32 v[38:39], 0
	v_mov_b64_e32 v[40:41], 0
	v_mov_b64_e32 v[42:43], 0
	v_mov_b64_e32 v[44:45], 0
	v_mov_b64_e32 v[46:47], 0
	v_mov_b64_e32 v[48:49], 0
	v_mov_b64_e32 v[50:51], 0
	v_mov_b64_e32 v[52:53], 0
	v_mov_b64_e32 v[54:55], 0
	v_mov_b64_e32 v[56:57], 0
	v_mov_b64_e32 v[58:59], 0
	v_mov_b64_e32 v[60:61], 0
	v_mov_b64_e32 v[62:63], 0
	v_mov_b64_e32 v[64:65], 0
	v_mov_b64_e32 v[66:67], 0
	v_mov_b64_e32 v[68:69], 0
	v_mov_b64_e32 v[70:71], 0
	v_mov_b64_e32 v[72:73], 0
	v_mov_b64_e32 v[74:75], 0
	v_mov_b64_e32 v[76:77], 0
	v_mov_b64_e32 v[78:79], 0
	v_mov_b64_e32 v[80:81], 0
	v_mov_b64_e32 v[82:83], 0
	v_mov_b64_e32 v[84:85], 0
	v_mov_b64_e32 v[86:87], 0
	v_mov_b64_e32 v[88:89], 0
	v_mov_b64_e32 v[90:91], 0
	v_mov_b64_e32 v[92:93], 0
	v_mov_b64_e32 v[94:95], 0
	v_mov_b64_e32 v[96:97], 0
	v_mov_b64_e32 v[98:99], 0
	v_mov_b64_e32 v[100:101], 0
	v_mov_b64_e32 v[102:103], 0
	v_mov_b64_e32 v[104:105], 0
	v_mov_b64_e32 v[106:107], 0
	v_mov_b64_e32 v[108:109], 0
	v_mov_b64_e32 v[110:111], 0
	v_mov_b64_e32 v[112:113], 0
	v_mov_b64_e32 v[114:115], 0
	v_mov_b64_e32 v[116:117], 0
	v_mov_b64_e32 v[118:119], 0
	v_mov_b64_e32 v[120:121], 0
	v_mov_b64_e32 v[122:123], 0
	v_mov_b64_e32 v[124:125], 0
	v_mov_b64_e32 v[126:127], 0
	v_mov_b64_e32 v[128:129], 0

; template <bool PERM, class SchedT, class Epi>
; __device__ __forceinline__ void gemm_phase(LAS unsigned char* lds, const SchedT& S, const Epi& E) {
;     ...
;         for (int a = 0; a < 2; ++a)
; #pragma unroll
;             for (int b = 0; b < 2; ++b)
; #pragma unroll
;                 for (int m = 0; m < 4; ++m)
; #pragma unroll
;                     for (int n = 0; n < 2; ++n) acc[a][b][m][n] = (f32x4){0.f, 0.f, 0.f, 0.f};
;         cur = nxt; cA = nA; cB = nB; lda = nlda; K = nK; ++ui;
.LBB0_164:
	s_xor_b64 s[20:21], s[24:25], -1
	s_and_b64 s[28:29], s[24:25], exec
	s_cselect_b32 s45, s17, s13
	s_cselect_b32 s46, s16, s12
	s_cselect_b32 s47, s11, s27
	s_cselect_b32 s48, s10, s26
	s_ashr_i32 s7, s6, 31
	s_lshl_b64 s[28:29], s[6:7], 8
	s_add_u32 s7, s26, 0x100
	s_addc_u32 s49, s27, 0
	v_mad_u64_u32 v[2:3], s[26:27], s6, v131, v[136:137]
	s_add_u32 s26, s12, s28
	s_addc_u32 s27, s13, s29
	s_add_u32 s26, s26, 0x80
	v_mov_b32_e32 v3, v1
	s_addc_u32 s27, s27, 0
	v_lshl_add_u64 v[140:141], s[26:27], 0, v[2:3]
	v_mad_u64_u32 v[2:3], s[28:29], s6, v133, v[138:139]
	v_mov_b32_e32 v3, v1
	v_lshl_add_u64 v[142:143], s[26:27], 0, v[2:3]
	s_mov_b32 s50, -2
	v_mov_b64_e32 v[2:3], 0
	v_mov_b64_e32 v[4:5], 0
	v_mov_b64_e32 v[6:7], 0
	v_mov_b64_e32 v[8:9], 0
	v_mov_b64_e32 v[10:11], 0
	v_mov_b64_e32 v[12:13], 0
	v_mov_b64_e32 v[14:15], 0
	v_mov_b64_e32 v[16:17], 0
	v_mov_b64_e32 v[18:19], 0
	v_mov_b64_e32 v[20:21], 0
	v_mov_b64_e32 v[22:23], 0
	v_mov_b64_e32 v[24:25], 0
	v_mov_b64_e32 v[26:27], 0
	v_mov_b64_e32 v[28:29], 0
	v_mov_b64_e32 v[30:31], 0
	v_mov_b64_e32 v[32:33], 0
	v_mov_b64_e32 v[34:35], 0
	v_mov_b64_e32 v[36:37], 0
	v_mov_b64_e32 v[38:39], 0
	v_mov_b64_e32 v[40:41], 0
	v_mov_b64_e32 v[42:43], 0
	v_mov_b64_e32 v[44:45], 0
	v_mov_b64_e32 v[46:47], 0
	v_mov_b64_e32 v[48:49], 0
	v_mov_b64_e32 v[50:51], 0
	v_mov_b64_e32 v[52:53], 0
	v_mov_b64_e32 v[54:55], 0
	v_mov_b64_e32 v[56:57], 0
	v_mov_b64_e32 v[58:59], 0
	v_mov_b64_e32 v[60:61], 0
	v_mov_b64_e32 v[62:63], 0
	v_mov_b64_e32 v[64:65], 0
	v_mov_b64_e32 v[66:67], 0
	v_mov_b64_e32 v[68:69], 0
	v_mov_b64_e32 v[70:71], 0
	v_mov_b64_e32 v[72:73], 0
	v_mov_b64_e32 v[74:75], 0
	v_mov_b64_e32 v[76:77], 0
	v_mov_b64_e32 v[78:79], 0
	v_mov_b64_e32 v[80:81], 0
	v_mov_b64_e32 v[82:83], 0
	v_mov_b64_e32 v[84:85], 0
	v_mov_b64_e32 v[86:87], 0
	v_mov_b64_e32 v[88:89], 0
	v_mov_b64_e32 v[90:91], 0
	v_mov_b64_e32 v[92:93], 0
	v_mov_b64_e32 v[94:95], 0
	v_mov_b64_e32 v[96:97], 0
	v_mov_b64_e32 v[98:99], 0
	v_mov_b64_e32 v[100:101], 0
	v_mov_b64_e32 v[102:103], 0
	v_mov_b64_e32 v[104:105], 0
	v_mov_b64_e32 v[106:107], 0
	v_mov_b64_e32 v[108:109], 0
	v_mov_b64_e32 v[110:111], 0
	v_mov_b64_e32 v[112:113], 0
	v_mov_b64_e32 v[114:115], 0
	v_mov_b64_e32 v[116:117], 0
	v_mov_b64_e32 v[118:119], 0
	v_mov_b64_e32 v[120:121], 0
	v_mov_b64_e32 v[122:123], 0
	v_mov_b64_e32 v[124:125], 0
	v_mov_b64_e32 v[126:127], 0
	v_mov_b64_e32 v[128:129], 0

; template <bool PERM, class SchedT, class Epi>
; __device__ __forceinline__ void gemm_phase(LAS unsigned char* lds, const SchedT& S, const Epi& E) {
;     ...
;         for (int a = 0; a < 2; ++a)
; #pragma unroll
;             for (int b = 0; b < 2; ++b)
; #pragma unroll
;                 for (int m = 0; m < 4; ++m)
; #pragma unroll
;                     for (int n = 0; n < 2; ++n) acc[a][b][m][n] = (f32x4){0.f, 0.f, 0.f, 0.f};
;         cur = nxt; cA = nA; cB = nB; lda = nlda; K = nK; ++ui;
.LBB0_248:
	s_add_u32 s8, s20, 0x80080
	s_addc_u32 s9, s21, 0
	s_add_u32 s11, s18, 0x100
	s_addc_u32 s13, s19, 0
	s_mov_b32 s34, -2
	v_mov_b64_e32 v[2:3], 0
	v_mov_b64_e32 v[4:5], 0
	v_mov_b64_e32 v[6:7], 0
	v_mov_b64_e32 v[8:9], 0
	v_mov_b64_e32 v[10:11], 0
	v_mov_b64_e32 v[12:13], 0
	v_mov_b64_e32 v[14:15], 0
	v_mov_b64_e32 v[16:17], 0
	v_mov_b64_e32 v[18:19], 0
	v_mov_b64_e32 v[20:21], 0
	v_mov_b64_e32 v[22:23], 0
	v_mov_b64_e32 v[24:25], 0
	v_mov_b64_e32 v[26:27], 0
	v_mov_b64_e32 v[28:29], 0
	v_mov_b64_e32 v[30:31], 0
	v_mov_b64_e32 v[32:33], 0
	v_mov_b64_e32 v[34:35], 0
	v_mov_b64_e32 v[36:37], 0
	v_mov_b64_e32 v[38:39], 0
	v_mov_b64_e32 v[40:41], 0
	v_mov_b64_e32 v[42:43], 0
	v_mov_b64_e32 v[44:45], 0
	v_mov_b64_e32 v[46:47], 0
	v_mov_b64_e32 v[48:49], 0
	v_mov_b64_e32 v[50:51], 0
	v_mov_b64_e32 v[52:53], 0
	v_mov_b64_e32 v[54:55], 0
	v_mov_b64_e32 v[56:57], 0
	v_mov_b64_e32 v[58:59], 0
	v_mov_b64_e32 v[60:61], 0
	v_mov_b64_e32 v[62:63], 0
	v_mov_b64_e32 v[64:65], 0
	v_mov_b64_e32 v[66:67], 0
	v_mov_b64_e32 v[68:69], 0
	v_mov_b64_e32 v[70:71], 0
	v_mov_b64_e32 v[72:73], 0
	v_mov_b64_e32 v[74:75], 0
	v_mov_b64_e32 v[76:77], 0
	v_mov_b64_e32 v[78:79], 0
	v_mov_b64_e32 v[80:81], 0
	v_mov_b64_e32 v[82:83], 0
	v_mov_b64_e32 v[84:85], 0
	v_mov_b64_e32 v[86:87], 0
	v_mov_b64_e32 v[88:89], 0
	v_mov_b64_e32 v[90:91], 0
	v_mov_b64_e32 v[92:93], 0
	v_mov_b64_e32 v[94:95], 0
	v_mov_b64_e32 v[96:97], 0
	v_mov_b64_e32 v[98:99], 0
	v_mov_b64_e32 v[100:101], 0
	v_mov_b64_e32 v[102:103], 0
	v_mov_b64_e32 v[104:105], 0
	v_mov_b64_e32 v[106:107], 0
	v_mov_b64_e32 v[108:109], 0
	v_mov_b64_e32 v[110:111], 0
	v_mov_b64_e32 v[112:113], 0
	v_mov_b64_e32 v[114:115], 0
	v_mov_b64_e32 v[116:117], 0
	v_mov_b64_e32 v[118:119], 0
	v_mov_b64_e32 v[120:121], 0
	v_mov_b64_e32 v[122:123], 0
	v_mov_b64_e32 v[124:125], 0
	v_mov_b64_e32 v[126:127], 0
	v_mov_b64_e32 v[128:129], 0

; template <bool PERM, class SchedT, class Epi>
; __device__ __forceinline__ void gemm_phase(LAS unsigned char* lds, const SchedT& S, const Epi& E) {
;     ...
;         for (int a = 0; a < 2; ++a)
; #pragma unroll
;             for (int b = 0; b < 2; ++b)
; #pragma unroll
;                 for (int m = 0; m < 4; ++m)
; #pragma unroll
;                     for (int n = 0; n < 2; ++n) acc[a][b][m][n] = (f32x4){0.f, 0.f, 0.f, 0.f};
;         cur = nxt; cA = nA; cB = nB; lda = nlda; K = nK; ++ui;
.LBB0_365:
	s_add_u32 s24, s24, 0x80080
	s_addc_u32 s25, s25, 0
	s_add_u32 s17, s26, 0x100
	s_addc_u32 s19, s27, 0
	s_mov_b32 s41, -2
	v_mov_b64_e32 v[2:3], 0
	v_mov_b64_e32 v[4:5], 0
	v_mov_b64_e32 v[6:7], 0
	v_mov_b64_e32 v[8:9], 0
	v_mov_b64_e32 v[10:11], 0
	v_mov_b64_e32 v[12:13], 0
	v_mov_b64_e32 v[14:15], 0
	v_mov_b64_e32 v[16:17], 0
	v_mov_b64_e32 v[18:19], 0
	v_mov_b64_e32 v[20:21], 0
	v_mov_b64_e32 v[22:23], 0
	v_mov_b64_e32 v[24:25], 0
	v_mov_b64_e32 v[26:27], 0
	v_mov_b64_e32 v[28:29], 0
	v_mov_b64_e32 v[30:31], 0
	v_mov_b64_e32 v[32:33], 0
	v_mov_b64_e32 v[34:35], 0
	v_mov_b64_e32 v[36:37], 0
	v_mov_b64_e32 v[38:39], 0
	v_mov_b64_e32 v[40:41], 0
	v_mov_b64_e32 v[42:43], 0
	v_mov_b64_e32 v[44:45], 0
	v_mov_b64_e32 v[46:47], 0
	v_mov_b64_e32 v[48:49], 0
	v_mov_b64_e32 v[50:51], 0
	v_mov_b64_e32 v[52:53], 0
	v_mov_b64_e32 v[54:55], 0
	v_mov_b64_e32 v[56:57], 0
	v_mov_b64_e32 v[58:59], 0
	v_mov_b64_e32 v[60:61], 0
	v_mov_b64_e32 v[62:63], 0
	v_mov_b64_e32 v[64:65], 0
	v_mov_b64_e32 v[66:67], 0
	v_mov_b64_e32 v[68:69], 0
	v_mov_b64_e32 v[70:71], 0
	v_mov_b64_e32 v[72:73], 0
	v_mov_b64_e32 v[74:75], 0
	v_mov_b64_e32 v[76:77], 0
	v_mov_b64_e32 v[78:79], 0
	v_mov_b64_e32 v[80:81], 0
	v_mov_b64_e32 v[82:83], 0
	v_mov_b64_e32 v[84:85], 0
	v_mov_b64_e32 v[86:87], 0
	v_mov_b64_e32 v[88:89], 0
	v_mov_b64_e32 v[90:91], 0
	v_mov_b64_e32 v[92:93], 0
	v_mov_b64_e32 v[94:95], 0
	v_mov_b64_e32 v[96:97], 0
	v_mov_b64_e32 v[98:99], 0
	v_mov_b64_e32 v[100:101], 0
	v_mov_b64_e32 v[102:103], 0
	v_mov_b64_e32 v[104:105], 0
	v_mov_b64_e32 v[106:107], 0
	v_mov_b64_e32 v[108:109], 0
	v_mov_b64_e32 v[110:111], 0
	v_mov_b64_e32 v[112:113], 0
	v_mov_b64_e32 v[114:115], 0
	v_mov_b64_e32 v[116:117], 0
	v_mov_b64_e32 v[118:119], 0
	v_mov_b64_e32 v[120:121], 0
	v_mov_b64_e32 v[122:123], 0
	v_mov_b64_e32 v[124:125], 0
	v_mov_b64_e32 v[126:127], 0
	v_mov_b64_e32 v[128:129], 0
